# nt stores for the SwiGLU epilogue output FF (P7, P14)
# baseline (speedup 1.0000x reference)
.LBB0_783:
	s_waitcnt vmcnt(0)
	v_mul_f32_e32 v158, 0xbfb8aa3b, v153
	v_pk_mul_f32 v[160:161], v[158:159], v[122:123] op_sel_hi:[0,1]
	v_pk_mul_f32 v[122:123], v[122:123], v[126:127]
	v_pk_mul_f32 v[126:127], v[158:159], v[112:113] op_sel_hi:[0,1]
	v_pk_mul_f32 v[162:163], v[158:159], v[120:121] op_sel_hi:[0,1]
	v_pk_mul_f32 v[120:121], v[120:121], v[124:125]
	v_pk_mul_f32 v[124:125], v[158:159], v[114:115] op_sel_hi:[0,1]
	v_exp_f32_e32 v126, v126
	v_exp_f32_e32 v127, v127
	v_exp_f32_e32 v162, v162
	v_exp_f32_e32 v163, v163
	v_exp_f32_e32 v160, v160
	v_exp_f32_e32 v161, v161
	v_exp_f32_e32 v124, v124
	v_exp_f32_e32 v125, v125
	v_mov_b32_e32 v138, v140
	v_mov_b32_e32 v139, v141
	v_pk_add_f32 v[126:127], v[126:127], 1.0 op_sel_hi:[1,0]
	v_pk_add_f32 v[160:161], v[160:161], 1.0 op_sel_hi:[1,0]
	v_add_u32_e32 v154, s45, v138
	s_lshl_b32 s45, s76, 7
	v_pk_add_f32 v[162:163], v[162:163], 1.0 op_sel_hi:[1,0]
	v_pk_add_f32 v[124:125], v[124:125], 1.0 op_sel_hi:[1,0]
	v_rcp_f32_e32 v126, v126
	v_rcp_f32_e32 v127, v127
	s_or_b32 s45, s45, s72
	v_rcp_f32_e32 v162, v162
	v_rcp_f32_e32 v163, v163
	v_rcp_f32_e32 v160, v160
	v_rcp_f32_e32 v161, v161
	v_rcp_f32_e32 v124, v124
	v_rcp_f32_e32 v125, v125
	v_lshl_add_u32 v156, v139, 3, s45
	v_mul_f32_e32 v166, v153, v153
	v_pk_mul_f32 v[112:113], v[112:113], v[116:117]
	v_ashrrev_i32_e32 v157, 31, v156
	v_mov_b64_e32 v[138:139], s[14:15]
	v_pk_mul_f32 v[114:115], v[114:115], v[118:119]
	v_pk_mul_f32 v[112:113], v[166:167], v[112:113] op_sel_hi:[0,1]
	v_mad_i64_i32 v[164:165], s[52:53], v154, s75, v[138:139]
	v_pk_mul_f32 v[120:121], v[166:167], v[120:121] op_sel_hi:[0,1]
	v_pk_mul_f32 v[122:123], v[166:167], v[122:123] op_sel_hi:[0,1]
	v_pk_mul_f32 v[114:115], v[166:167], v[114:115] op_sel_hi:[0,1]
	v_pk_mul_f32 v[116:117], v[126:127], v[112:113]
	v_lshlrev_b64 v[112:113], 1, v[156:157]
	v_pk_mul_f32 v[122:123], v[160:161], v[122:123]
	v_pk_mul_f32 v[120:121], v[162:163], v[120:121]
	v_pk_mul_f32 v[118:119], v[124:125], v[114:115]
	v_lshl_add_u64 v[124:125], v[164:165], 0, v[112:113]
	v_cvt_pk_bf16_f32 v114, v120, v121
	v_cvt_pk_bf16_f32 v115, v122, v123
	v_cvt_pk_bf16_f32 v116, v116, v117
	v_cvt_pk_bf16_f32 v117, v118, v119
	global_store_dwordx4 v[124:125], v[114:117], off nt
	v_mul_f32_e32 v122, v152, v152
	s_andn2_b64 vcc, exec, s[4:5]
	v_add_u32_e32 v115, 16, v154
	v_mul_f32_e32 v114, 0xbfb8aa3b, v152
	v_pk_mul_f32 v[116:117], v[114:115], v[106:107] op_sel_hi:[0,1]
	v_pk_mul_f32 v[118:119], v[114:115], v[104:105] op_sel_hi:[0,1]
	v_pk_mul_f32 v[106:107], v[106:107], v[110:111]
	v_pk_mul_f32 v[104:105], v[104:105], v[108:109]
	v_pk_mul_f32 v[108:109], v[114:115], v[98:99] op_sel_hi:[0,1]
	v_pk_mul_f32 v[110:111], v[114:115], v[96:97] op_sel_hi:[0,1]
	v_exp_f32_e32 v118, v118
	v_exp_f32_e32 v119, v119
	v_exp_f32_e32 v116, v116
	v_exp_f32_e32 v117, v117
	v_exp_f32_e32 v110, v110
	v_exp_f32_e32 v108, v108
	v_exp_f32_e32 v109, v109
	v_exp_f32_e32 v111, v111
	v_pk_add_f32 v[116:117], v[116:117], 1.0 op_sel_hi:[1,0]
	v_pk_add_f32 v[118:119], v[118:119], 1.0 op_sel_hi:[1,0]
	v_pk_add_f32 v[108:109], v[108:109], 1.0 op_sel_hi:[1,0]
	v_pk_add_f32 v[110:111], v[110:111], 1.0 op_sel_hi:[1,0]
	v_rcp_f32_e32 v118, v118
	v_rcp_f32_e32 v119, v119
	v_rcp_f32_e32 v116, v116
	v_rcp_f32_e32 v117, v117
	v_rcp_f32_e32 v110, v110
	v_rcp_f32_e32 v111, v111
	v_rcp_f32_e32 v108, v108
	v_rcp_f32_e32 v109, v109
	v_pk_mul_f32 v[98:99], v[98:99], v[102:103]
	v_pk_mul_f32 v[96:97], v[96:97], v[100:101]
	v_mad_i64_i32 v[120:121], s[52:53], v115, s75, v[138:139]
	v_pk_mul_f32 v[104:105], v[122:123], v[104:105] op_sel_hi:[0,1]
	v_pk_mul_f32 v[106:107], v[122:123], v[106:107] op_sel_hi:[0,1]
	v_pk_mul_f32 v[96:97], v[122:123], v[96:97] op_sel_hi:[0,1]
	v_pk_mul_f32 v[98:99], v[122:123], v[98:99] op_sel_hi:[0,1]
	v_pk_mul_f32 v[106:107], v[116:117], v[106:107]
	v_pk_mul_f32 v[104:105], v[118:119], v[104:105]
	v_pk_mul_f32 v[100:101], v[108:109], v[98:99]
	v_pk_mul_f32 v[98:99], v[110:111], v[96:97]
	v_lshl_add_u64 v[102:103], v[120:121], 0, v[112:113]
	v_cvt_pk_bf16_f32 v96, v104, v105
	v_cvt_pk_bf16_f32 v97, v106, v107
	v_cvt_pk_bf16_f32 v98, v98, v99
	v_cvt_pk_bf16_f32 v99, v100, v101
	global_store_dwordx4 v[102:103], v[96:99], off nt
	v_mul_f32_e32 v104, v151, v151
	s_mov_b64 s[4:5], -1
	v_add_u32_e32 v97, 32, v154
	v_mul_f32_e32 v96, 0xbfb8aa3b, v151
	v_pk_mul_f32 v[98:99], v[96:97], v[90:91] op_sel_hi:[0,1]
	v_pk_mul_f32 v[100:101], v[96:97], v[88:89] op_sel_hi:[0,1]
	v_pk_mul_f32 v[90:91], v[90:91], v[94:95]
	v_pk_mul_f32 v[88:89], v[88:89], v[92:93]
	v_pk_mul_f32 v[92:93], v[96:97], v[82:83] op_sel_hi:[0,1]
	v_pk_mul_f32 v[94:95], v[96:97], v[80:81] op_sel_hi:[0,1]
	v_exp_f32_e32 v100, v100
	v_exp_f32_e32 v101, v101
	v_exp_f32_e32 v98, v98
	v_exp_f32_e32 v99, v99
	v_exp_f32_e32 v94, v94
	v_exp_f32_e32 v92, v92
	v_exp_f32_e32 v93, v93
	v_exp_f32_e32 v95, v95
	v_pk_add_f32 v[98:99], v[98:99], 1.0 op_sel_hi:[1,0]
	v_pk_add_f32 v[100:101], v[100:101], 1.0 op_sel_hi:[1,0]
	v_pk_add_f32 v[92:93], v[92:93], 1.0 op_sel_hi:[1,0]
	v_pk_add_f32 v[94:95], v[94:95], 1.0 op_sel_hi:[1,0]
	v_rcp_f32_e32 v100, v100
	v_rcp_f32_e32 v101, v101
	v_rcp_f32_e32 v98, v98
	v_rcp_f32_e32 v99, v99
	v_rcp_f32_e32 v94, v94
	v_rcp_f32_e32 v95, v95
	v_rcp_f32_e32 v92, v92
	v_rcp_f32_e32 v93, v93
	v_pk_mul_f32 v[82:83], v[82:83], v[86:87]
	v_pk_mul_f32 v[80:81], v[80:81], v[84:85]
	v_mad_i64_i32 v[102:103], s[52:53], v97, s75, v[138:139]
	v_pk_mul_f32 v[88:89], v[104:105], v[88:89] op_sel_hi:[0,1]
	v_pk_mul_f32 v[90:91], v[104:105], v[90:91] op_sel_hi:[0,1]
	v_pk_mul_f32 v[80:81], v[104:105], v[80:81] op_sel_hi:[0,1]
	v_pk_mul_f32 v[82:83], v[104:105], v[82:83] op_sel_hi:[0,1]
	v_pk_mul_f32 v[90:91], v[98:99], v[90:91]
	v_pk_mul_f32 v[88:89], v[100:101], v[88:89]
	v_pk_mul_f32 v[84:85], v[92:93], v[82:83]
	v_pk_mul_f32 v[82:83], v[94:95], v[80:81]
	v_lshl_add_u64 v[86:87], v[102:103], 0, v[112:113]
	v_cvt_pk_bf16_f32 v80, v88, v89
	v_cvt_pk_bf16_f32 v81, v90, v91
	v_cvt_pk_bf16_f32 v82, v82, v83
	v_cvt_pk_bf16_f32 v83, v84, v85
	global_store_dwordx4 v[86:87], v[80:83], off nt
	v_mul_f32_e32 v88, v150, v150
	s_nop 0
	v_add_u32_e32 v81, 48, v154
	v_mul_f32_e32 v80, 0xbfb8aa3b, v150
	v_pk_mul_f32 v[82:83], v[80:81], v[74:75] op_sel_hi:[0,1]
	v_pk_mul_f32 v[84:85], v[80:81], v[72:73] op_sel_hi:[0,1]
	v_pk_mul_f32 v[74:75], v[74:75], v[78:79]
	v_pk_mul_f32 v[72:73], v[72:73], v[76:77]
	v_pk_mul_f32 v[76:77], v[80:81], v[58:59] op_sel_hi:[0,1]
	v_pk_mul_f32 v[78:79], v[80:81], v[56:57] op_sel_hi:[0,1]
	v_exp_f32_e32 v84, v84
	v_exp_f32_e32 v85, v85
	v_exp_f32_e32 v82, v82
	v_exp_f32_e32 v83, v83
	v_exp_f32_e32 v78, v78
	v_exp_f32_e32 v76, v76
	v_exp_f32_e32 v77, v77
	v_exp_f32_e32 v79, v79
	v_pk_add_f32 v[82:83], v[82:83], 1.0 op_sel_hi:[1,0]
	v_pk_add_f32 v[84:85], v[84:85], 1.0 op_sel_hi:[1,0]
	v_pk_add_f32 v[76:77], v[76:77], 1.0 op_sel_hi:[1,0]
	v_pk_add_f32 v[78:79], v[78:79], 1.0 op_sel_hi:[1,0]
	v_rcp_f32_e32 v84, v84
	v_rcp_f32_e32 v85, v85
	v_rcp_f32_e32 v82, v82
	v_rcp_f32_e32 v83, v83
	v_rcp_f32_e32 v78, v78
	v_rcp_f32_e32 v79, v79
	v_rcp_f32_e32 v76, v76
	v_rcp_f32_e32 v77, v77
	v_pk_mul_f32 v[58:59], v[58:59], v[66:67]
	v_pk_mul_f32 v[56:57], v[56:57], v[64:65]
	v_mad_i64_i32 v[86:87], s[52:53], v81, s75, v[138:139]
	v_pk_mul_f32 v[72:73], v[88:89], v[72:73] op_sel_hi:[0,1]
	v_pk_mul_f32 v[74:75], v[88:89], v[74:75] op_sel_hi:[0,1]
	v_pk_mul_f32 v[56:57], v[88:89], v[56:57] op_sel_hi:[0,1]
	v_pk_mul_f32 v[58:59], v[88:89], v[58:59] op_sel_hi:[0,1]
	v_pk_mul_f32 v[74:75], v[82:83], v[74:75]
	v_pk_mul_f32 v[72:73], v[84:85], v[72:73]
	v_pk_mul_f32 v[64:65], v[76:77], v[58:59]
	v_pk_mul_f32 v[58:59], v[78:79], v[56:57]
	v_lshl_add_u64 v[66:67], v[86:87], 0, v[112:113]
	v_cvt_pk_bf16_f32 v56, v72, v73
	v_cvt_pk_bf16_f32 v57, v74, v75
	v_cvt_pk_bf16_f32 v58, v58, v59
	v_cvt_pk_bf16_f32 v59, v64, v65
	global_store_dwordx4 v[66:67], v[56:59], off nt
	v_mul_f32_e32 v72, v149, v149
	s_nop 0
	v_add_u32_e32 v57, 0x80, v154
	v_mul_f32_e32 v56, 0xbfb8aa3b, v149
	v_pk_mul_f32 v[58:59], v[56:57], v[62:63] op_sel_hi:[0,1]
	v_exp_f32_e32 v58, v58
	v_exp_f32_e32 v59, v59
	v_pk_mul_f32 v[64:65], v[56:57], v[60:61] op_sel_hi:[0,1]
	v_mad_i64_i32 v[66:67], s[52:53], v57, s75, v[138:139]
	v_pk_add_f32 v[58:59], v[58:59], 1.0 op_sel_hi:[1,0]
	v_pk_mul_f32 v[60:61], v[60:61], v[68:69]
	v_pk_mul_f32 v[68:69], v[56:57], v[50:51] op_sel_hi:[0,1]
	v_pk_mul_f32 v[56:57], v[56:57], v[48:49] op_sel_hi:[0,1]
	v_exp_f32_e32 v64, v64
	v_exp_f32_e32 v65, v65
	v_rcp_f32_e32 v58, v58
	v_rcp_f32_e32 v59, v59
	v_exp_f32_e32 v56, v56
	v_exp_f32_e32 v68, v68
	v_exp_f32_e32 v69, v69
	v_exp_f32_e32 v57, v57
	v_pk_mul_f32 v[62:63], v[62:63], v[70:71]
	v_pk_add_f32 v[64:65], v[64:65], 1.0 op_sel_hi:[1,0]
	v_pk_mul_f32 v[62:63], v[72:73], v[62:63] op_sel_hi:[0,1]
	v_pk_mul_f32 v[58:59], v[58:59], v[62:63]
	v_pk_add_f32 v[62:63], v[68:69], 1.0 op_sel_hi:[1,0]
	v_pk_add_f32 v[56:57], v[56:57], 1.0 op_sel_hi:[1,0]
	v_rcp_f32_e32 v64, v64
	v_rcp_f32_e32 v65, v65
	v_rcp_f32_e32 v56, v56
	v_rcp_f32_e32 v57, v57
	v_rcp_f32_e32 v62, v62
	v_rcp_f32_e32 v63, v63
	v_pk_mul_f32 v[50:51], v[50:51], v[54:55]
	v_pk_mul_f32 v[48:49], v[48:49], v[52:53]
	v_pk_mul_f32 v[60:61], v[72:73], v[60:61] op_sel_hi:[0,1]
	v_pk_mul_f32 v[48:49], v[72:73], v[48:49] op_sel_hi:[0,1]
	v_pk_mul_f32 v[50:51], v[72:73], v[50:51] op_sel_hi:[0,1]
	v_pk_mul_f32 v[60:61], v[64:65], v[60:61]
	v_pk_mul_f32 v[52:53], v[62:63], v[50:51]
	v_pk_mul_f32 v[50:51], v[56:57], v[48:49]
	v_lshl_add_u64 v[54:55], v[66:67], 0, v[112:113]
	v_cvt_pk_bf16_f32 v48, v60, v61
	v_cvt_pk_bf16_f32 v49, v58, v59
	v_cvt_pk_bf16_f32 v50, v50, v51
	v_cvt_pk_bf16_f32 v51, v52, v53
	global_store_dwordx4 v[54:55], v[48:51], off nt
	v_mul_f32_e32 v56, v148, v148
	s_nop 0
	v_add_u32_e32 v49, 0x90, v154
	v_mul_f32_e32 v48, 0xbfb8aa3b, v148
	v_pk_mul_f32 v[50:51], v[48:49], v[42:43] op_sel_hi:[0,1]
	v_pk_mul_f32 v[52:53], v[48:49], v[40:41] op_sel_hi:[0,1]
	v_pk_mul_f32 v[42:43], v[42:43], v[46:47]
	v_pk_mul_f32 v[40:41], v[40:41], v[44:45]
	v_pk_mul_f32 v[44:45], v[48:49], v[34:35] op_sel_hi:[0,1]
	v_pk_mul_f32 v[46:47], v[48:49], v[32:33] op_sel_hi:[0,1]
	v_exp_f32_e32 v52, v52
	v_exp_f32_e32 v53, v53
	v_exp_f32_e32 v50, v50
	v_exp_f32_e32 v51, v51
	v_exp_f32_e32 v46, v46
	v_exp_f32_e32 v44, v44
	v_exp_f32_e32 v45, v45
	v_exp_f32_e32 v47, v47
	v_pk_add_f32 v[50:51], v[50:51], 1.0 op_sel_hi:[1,0]
	v_pk_add_f32 v[52:53], v[52:53], 1.0 op_sel_hi:[1,0]
	v_pk_add_f32 v[44:45], v[44:45], 1.0 op_sel_hi:[1,0]
	v_pk_add_f32 v[46:47], v[46:47], 1.0 op_sel_hi:[1,0]
	v_rcp_f32_e32 v52, v52
	v_rcp_f32_e32 v53, v53
	v_rcp_f32_e32 v50, v50
	v_rcp_f32_e32 v51, v51
	v_rcp_f32_e32 v46, v46
	v_rcp_f32_e32 v47, v47
	v_rcp_f32_e32 v44, v44
	v_rcp_f32_e32 v45, v45
	v_pk_mul_f32 v[34:35], v[34:35], v[38:39]
	v_pk_mul_f32 v[32:33], v[32:33], v[36:37]
	v_mad_i64_i32 v[54:55], s[52:53], v49, s75, v[138:139]
	v_pk_mul_f32 v[40:41], v[56:57], v[40:41] op_sel_hi:[0,1]
	v_pk_mul_f32 v[42:43], v[56:57], v[42:43] op_sel_hi:[0,1]
	v_pk_mul_f32 v[32:33], v[56:57], v[32:33] op_sel_hi:[0,1]
	v_pk_mul_f32 v[34:35], v[56:57], v[34:35] op_sel_hi:[0,1]
	v_pk_mul_f32 v[42:43], v[50:51], v[42:43]
	v_pk_mul_f32 v[40:41], v[52:53], v[40:41]
	v_pk_mul_f32 v[36:37], v[44:45], v[34:35]
	v_pk_mul_f32 v[34:35], v[46:47], v[32:33]
	v_lshl_add_u64 v[38:39], v[54:55], 0, v[112:113]
	v_cvt_pk_bf16_f32 v32, v40, v41
	v_cvt_pk_bf16_f32 v33, v42, v43
	v_cvt_pk_bf16_f32 v34, v34, v35
	v_cvt_pk_bf16_f32 v35, v36, v37
	global_store_dwordx4 v[38:39], v[32:35], off nt
	v_mul_f32_e32 v40, v147, v147
	s_nop 0
	v_add_u32_e32 v33, 0xa0, v154
	v_mul_f32_e32 v32, 0xbfb8aa3b, v147
	v_pk_mul_f32 v[34:35], v[32:33], v[26:27] op_sel_hi:[0,1]
	v_pk_mul_f32 v[36:37], v[32:33], v[24:25] op_sel_hi:[0,1]
	v_pk_mul_f32 v[26:27], v[26:27], v[30:31]
	v_pk_mul_f32 v[24:25], v[24:25], v[28:29]
	v_pk_mul_f32 v[28:29], v[32:33], v[18:19] op_sel_hi:[0,1]
	v_pk_mul_f32 v[30:31], v[32:33], v[16:17] op_sel_hi:[0,1]
	v_exp_f32_e32 v36, v36
	v_exp_f32_e32 v37, v37
	v_exp_f32_e32 v34, v34
	v_exp_f32_e32 v35, v35
	v_exp_f32_e32 v30, v30
	v_exp_f32_e32 v28, v28
	v_exp_f32_e32 v29, v29
	v_exp_f32_e32 v31, v31
	v_pk_add_f32 v[34:35], v[34:35], 1.0 op_sel_hi:[1,0]
	v_pk_add_f32 v[36:37], v[36:37], 1.0 op_sel_hi:[1,0]
	v_pk_add_f32 v[28:29], v[28:29], 1.0 op_sel_hi:[1,0]
	v_pk_add_f32 v[30:31], v[30:31], 1.0 op_sel_hi:[1,0]
	v_rcp_f32_e32 v36, v36
	v_rcp_f32_e32 v37, v37
	v_rcp_f32_e32 v34, v34
	v_rcp_f32_e32 v35, v35
	v_rcp_f32_e32 v30, v30
	v_rcp_f32_e32 v31, v31
	v_rcp_f32_e32 v28, v28
	v_rcp_f32_e32 v29, v29
	v_pk_mul_f32 v[18:19], v[18:19], v[22:23]
	v_pk_mul_f32 v[16:17], v[16:17], v[20:21]
	v_mad_i64_i32 v[38:39], s[52:53], v33, s75, v[138:139]
	v_pk_mul_f32 v[24:25], v[40:41], v[24:25] op_sel_hi:[0,1]
	v_pk_mul_f32 v[26:27], v[40:41], v[26:27] op_sel_hi:[0,1]
	v_pk_mul_f32 v[16:17], v[40:41], v[16:17] op_sel_hi:[0,1]
	v_pk_mul_f32 v[18:19], v[40:41], v[18:19] op_sel_hi:[0,1]
	v_pk_mul_f32 v[26:27], v[34:35], v[26:27]
	v_pk_mul_f32 v[24:25], v[36:37], v[24:25]
	v_pk_mul_f32 v[20:21], v[28:29], v[18:19]
	v_pk_mul_f32 v[18:19], v[30:31], v[16:17]
	v_lshl_add_u64 v[22:23], v[38:39], 0, v[112:113]
	v_cvt_pk_bf16_f32 v16, v24, v25
	v_cvt_pk_bf16_f32 v17, v26, v27
	v_cvt_pk_bf16_f32 v18, v18, v19
	v_cvt_pk_bf16_f32 v19, v20, v21
	global_store_dwordx4 v[22:23], v[16:19], off nt
	v_mul_f32_e32 v24, v146, v146
	s_nop 0
	v_add_u32_e32 v17, 0xb0, v154
	v_mul_f32_e32 v16, 0xbfb8aa3b, v146
	v_pk_mul_f32 v[18:19], v[16:17], v[10:11] op_sel_hi:[0,1]
	v_pk_mul_f32 v[20:21], v[16:17], v[8:9] op_sel_hi:[0,1]
	v_pk_mul_f32 v[10:11], v[10:11], v[14:15]
	v_pk_mul_f32 v[8:9], v[8:9], v[12:13]
	v_pk_mul_f32 v[12:13], v[16:17], v[2:3] op_sel_hi:[0,1]
	v_pk_mul_f32 v[14:15], v[16:17], v[0:1] op_sel_hi:[0,1]
	v_exp_f32_e32 v14, v14
	v_exp_f32_e32 v12, v12
	v_exp_f32_e32 v13, v13
	v_exp_f32_e32 v15, v15
	v_exp_f32_e32 v20, v20
	v_exp_f32_e32 v21, v21
	v_exp_f32_e32 v18, v18
	v_exp_f32_e32 v19, v19
	v_pk_add_f32 v[12:13], v[12:13], 1.0 op_sel_hi:[1,0]
	v_pk_add_f32 v[14:15], v[14:15], 1.0 op_sel_hi:[1,0]
	v_pk_add_f32 v[20:21], v[20:21], 1.0 op_sel_hi:[1,0]
	v_pk_add_f32 v[18:19], v[18:19], 1.0 op_sel_hi:[1,0]
	v_rcp_f32_e32 v14, v14
	v_rcp_f32_e32 v15, v15
	v_rcp_f32_e32 v12, v12
	v_rcp_f32_e32 v13, v13
	v_rcp_f32_e32 v20, v20
	v_rcp_f32_e32 v21, v21
	v_rcp_f32_e32 v18, v18
	v_rcp_f32_e32 v19, v19
	v_pk_mul_f32 v[2:3], v[2:3], v[6:7]
	v_pk_mul_f32 v[0:1], v[0:1], v[4:5]
	v_mad_i64_i32 v[22:23], s[52:53], v17, s75, v[138:139]
	v_pk_mul_f32 v[0:1], v[24:25], v[0:1] op_sel_hi:[0,1]
	v_pk_mul_f32 v[2:3], v[24:25], v[2:3] op_sel_hi:[0,1]
	v_pk_mul_f32 v[8:9], v[24:25], v[8:9] op_sel_hi:[0,1]
	v_pk_mul_f32 v[10:11], v[24:25], v[10:11] op_sel_hi:[0,1]
	v_pk_mul_f32 v[4:5], v[12:13], v[2:3]
	v_pk_mul_f32 v[2:3], v[14:15], v[0:1]
	v_lshl_add_u64 v[6:7], v[22:23], 0, v[112:113]
	v_pk_mul_f32 v[10:11], v[18:19], v[10:11]
	v_pk_mul_f32 v[8:9], v[20:21], v[8:9]
	s_nop 0
	v_cvt_pk_bf16_f32 v0, v8, v9
	v_cvt_pk_bf16_f32 v1, v10, v11
	v_cvt_pk_bf16_f32 v2, v2, v3
	v_cvt_pk_bf16_f32 v3, v4, v5
	global_store_dwordx4 v[6:7], v[0:3], off nt
	s_cbranch_vccnz .LBB0_776
	s_andn2_b64 vcc, exec, s[12:13]
	s_cbranch_vccnz .LBB0_775
	s_barrier
	s_branch .LBB0_775
